# K loop: s_setprio 1 before the pre-compute barrier and s_setprio 0 right after the last MFMA (before the post-compute barrier), so only the waking half holds priority at each release
# baseline (speedup 1.0000x reference)
; #define PG8_STAGE(bufoff, gbase, voff) do { _Pragma("unroll") for (int _i = 0; _i < 2; ++_i) \
;         __builtin_amdgcn_global_load_lds((const unsigned*)((const char*)(gbase) + (voff)[_i]), (PG8_LAS unsigned*)(lds + (bufoff) + ldsw + _i * 8192), 16, 0, 0); } while (0)
; #define PG8_LDA(dst, b, h) do { _Pragma("unroll") for (int m = 0; m < 4; ++m) _Pragma("unroll") for (int k = 0; k < 2; ++k) dst[m][k] = *(const PG8_LAS bf16x8*)(lds + PG8_SA(b, h) + aoff + m * 2048 + k * 1024); } while (0)
; #define PG8_LDB(dst, b, h) do { _Pragma("unroll") for (int n = 0; n < 2; ++n) _Pragma("unroll") for (int k = 0; k < 2; ++k) dst[n][k] = *(const PG8_LAS bf16x8*)(lds + PG8_SB(b, h) + boff + n * 2048 + k * 1024); } while (0)
; #define PG8_MMA(ai, bj, At, Bt) do { __builtin_amdgcn_s_setprio(1); _Pragma("unroll") for (int m = 0; m < 4; ++m) _Pragma("unroll") for (int n = 0; n < 2; ++n) _Pragma("unroll") for (int k = 0; k < 2; ++k) \
;         acc[ai][bj][m][n] = __builtin_amdgcn_mfma_f32_16x16x32_bf16(Bt[n][k], At[m][k], acc[ai][bj][m][n], 0, 0, 0); __builtin_amdgcn_s_setprio(0); } while (0)
; #define PG8_WAIT_V(n) asm volatile("s_waitcnt vmcnt(" #n ")" ::: "memory")
; #define PG8_BAR __builtin_amdgcn_s_barrier()
; template <class Epi, class Sched, bool ALIGN_EPI = false, bool SP2 = false>
; __device__ __forceinline__ void gemm_phase(PG8_LAS unsigned char* lds, const Gemm g, const Sched& S, const Epi& E) {
;     ...
;         for (int t = 0; t < nt; t += 2) {
;             const bool last = (t == nt - 2);
;             const char* a1 = cA + (size_t)(t + 1) * kstep;
;             const char* a2 = last ? nA : cA + (size_t)(t + 2) * kstep; const char* b2 = last ? nB : cB + (size_t)(t + 2) * kstep;
;             const char* a3 = a2 + kstep; const char* b3 = b2 + kstep;
;             if (last && has_next) S.a_ready(nxt);
;             if constexpr (SP2) {
;             PG8_LDB(B0, 0, 0); PG8_LDB(B1, 0, 1); PG8_SCHED; PG8_LDA(At, 0, 0); PG8_STAGE(PG8_SA(1, 1), a1 + hstep, voffA);
;             PG8_WAIT_V(8); PG8_WAIT_L(0); PG8_BAR; PG8_MMA(0, 0, At, B0); PG8_MMA(0, 1, At, B1); PG8_BAR; PG8_SCHED;
;             PG8_LDA(At, 0, 1); PG8_STAGE(PG8_SB(0, 0), b2, voffB); PG8_STAGE(PG8_SB(0, 1), b2 + hstep, voffB); PG8_STAGE(PG8_SA(0, 0), a2, voffA);
;             PG8_WAIT_V(8); PG8_WAIT_L(0); PG8_BAR; PG8_MMA(1, 0, At, B0); PG8_MMA(1, 1, At, B1); PG8_BAR; PG8_SCHED;
.LBB0_321:
	s_add_u32 s12, s16, 0x80
	s_addc_u32 s13, s17, 0
	s_add_u32 s16, s14, 0x100
	s_addc_u32 s17, s15, 0
	s_mov_b32 s14, 0
	s_nop 0
	s_nop 0
	s_waitcnt lgkmcnt(0)
	s_add_i32 s42, s14, 2
	s_add_u32 s43, s12, 0x80
	s_addc_u32 s15, s13, 0
	s_add_i32 s75, 0, 0x10000
	s_cmp_eq_u32 s25, s14
	s_cselect_b32 s15, s55, s15
	s_cselect_b32 s14, s54, s43
	s_cselect_b32 vcc_hi, s65, s17
	s_cselect_b32 vcc_lo, s64, s16
	s_add_i32 s43, 0, 0x14000
	v_add_u32_e32 v142, s75, v199
	v_add_u32_e32 v178, s43, v199
	ds_read_b128 v[130:133], v142
	ds_read_b128 v[134:137], v142 offset:1024
	ds_read_b128 v[138:141], v142 offset:2048
	ds_read_b128 v[142:145], v142 offset:3072
	ds_read_b128 v[170:173], v178
	ds_read_b128 v[174:177], v178 offset:1024
	ds_read_b128 v[202:205], v178 offset:2048
	ds_read_b128 v[206:209], v178 offset:3072
	v_lshl_add_u64 v[178:179], s[12:13], 0, v[166:167]
	s_add_i32 m0, s56, 0xc000
	ds_read_b128 v[210:213], v201
	ds_read_b128 v[214:217], v201 offset:1024
	ds_read_b128 v[218:221], v201 offset:2048
	ds_read_b128 v[222:225], v201 offset:3072
	ds_read_b128 v[226:229], v201 offset:4096
	ds_read_b128 v[230:233], v201 offset:5120
	ds_read_b128 v[234:237], v201 offset:6144
	ds_read_b128 v[238:241], v201 offset:7168
	global_load_lds_dwordx4 v[178:179], off
	v_lshl_add_u64 v[178:179], s[12:13], 0, v[168:169]
	s_add_i32 m0, s56, 0xe000
	s_nop 0
	global_load_lds_dwordx4 v[178:179], off
	s_waitcnt vmcnt(8)
	s_waitcnt lgkmcnt(0)
	s_setprio 1
	s_barrier
	v_mfma_f32_16x16x32_bf16 v[126:129], v[130:133], v[210:213], 0
	v_mfma_f32_16x16x32_bf16 v[126:129], v[134:137], v[214:217], v[126:129]
	v_mfma_f32_16x16x32_bf16 v[122:125], v[138:141], v[210:213], 0
	v_mfma_f32_16x16x32_bf16 v[122:125], v[142:145], v[214:217], v[122:125]
	v_mfma_f32_16x16x32_bf16 v[110:113], v[130:133], v[218:221], 0
	v_mfma_f32_16x16x32_bf16 v[110:113], v[134:137], v[222:225], v[110:113]
	v_mfma_f32_16x16x32_bf16 v[106:109], v[138:141], v[218:221], 0
	v_mfma_f32_16x16x32_bf16 v[106:109], v[142:145], v[222:225], v[106:109]
	v_mfma_f32_16x16x32_bf16 v[94:97], v[130:133], v[226:229], 0
	v_mfma_f32_16x16x32_bf16 v[94:97], v[134:137], v[230:233], v[94:97]
	v_mfma_f32_16x16x32_bf16 v[90:93], v[138:141], v[226:229], 0
	v_mfma_f32_16x16x32_bf16 v[90:93], v[142:145], v[230:233], v[90:93]
	v_mfma_f32_16x16x32_bf16 v[78:81], v[130:133], v[234:237], 0
	v_mfma_f32_16x16x32_bf16 v[78:81], v[134:137], v[238:241], v[78:81]
	v_mfma_f32_16x16x32_bf16 v[74:77], v[138:141], v[234:237], 0
	v_mfma_f32_16x16x32_bf16 v[74:77], v[142:145], v[238:241], v[74:77]
	v_mfma_f32_16x16x32_bf16 v[118:121], v[170:173], v[210:213], 0
	v_mfma_f32_16x16x32_bf16 v[118:121], v[174:177], v[214:217], v[118:121]
	v_mfma_f32_16x16x32_bf16 v[114:117], v[202:205], v[210:213], 0
	v_mfma_f32_16x16x32_bf16 v[114:117], v[206:209], v[214:217], v[114:117]
	v_mfma_f32_16x16x32_bf16 v[102:105], v[170:173], v[218:221], 0
	v_mfma_f32_16x16x32_bf16 v[102:105], v[174:177], v[222:225], v[102:105]
	v_mfma_f32_16x16x32_bf16 v[98:101], v[202:205], v[218:221], 0
	v_mfma_f32_16x16x32_bf16 v[98:101], v[206:209], v[222:225], v[98:101]
	v_mfma_f32_16x16x32_bf16 v[86:89], v[170:173], v[226:229], 0
	v_mfma_f32_16x16x32_bf16 v[86:89], v[174:177], v[230:233], v[86:89]
	v_mfma_f32_16x16x32_bf16 v[82:85], v[202:205], v[226:229], 0
	v_mfma_f32_16x16x32_bf16 v[82:85], v[206:209], v[230:233], v[82:85]
	v_mfma_f32_16x16x32_bf16 v[70:73], v[170:173], v[234:237], 0
	v_mfma_f32_16x16x32_bf16 v[70:73], v[174:177], v[238:241], v[70:73]
	v_mfma_f32_16x16x32_bf16 v[66:69], v[202:205], v[234:237], 0
	v_mfma_f32_16x16x32_bf16 v[66:69], v[206:209], v[238:241], v[66:69]
	s_setprio 0
	s_barrier
	s_add_i32 s75, s75, s23
	v_lshl_add_u64 v[178:179], vcc, 0, v[0:1]
	s_mov_b32 m0, s75
	ds_read_b128 v[210:213], v201 offset:16384
	ds_read_b128 v[214:217], v201 offset:17408
	ds_read_b128 v[218:221], v201 offset:18432
	ds_read_b128 v[222:225], v201 offset:19456
	ds_read_b128 v[226:229], v201 offset:20480
	ds_read_b128 v[230:233], v201 offset:21504
	ds_read_b128 v[234:237], v201 offset:22528
	ds_read_b128 v[238:241], v201 offset:23552
	global_load_lds_dwordx4 v[178:179], off
	s_add_i32 m0, s75, 0x2000
	v_lshl_add_u64 v[242:243], vcc, 0, v[162:163]
	s_add_u32 vcc_lo, vcc_lo, s84
	s_addc_u32 vcc_hi, vcc_hi, 0
	s_add_i32 s43, s43, s23
	global_load_lds_dwordx4 v[242:243], off
	v_lshl_add_u64 v[244:245], vcc, 0, v[0:1]
	s_mov_b32 m0, s43
	v_lshl_add_u64 v[246:247], vcc, 0, v[162:163]
	global_load_lds_dwordx4 v[244:245], off
	s_add_i32 m0, s43, 0x2000
	v_lshl_add_u64 v[248:249], s[14:15], 0, v[158:159]
	global_load_lds_dwordx4 v[246:247], off
	s_mov_b32 m0, s56
	v_lshl_add_u64 v[250:251], s[14:15], 0, v[160:161]
	global_load_lds_dwordx4 v[248:249], off
	s_mov_b32 m0, s82
	s_nop 0
	global_load_lds_dwordx4 v[250:251], off
	s_waitcnt vmcnt(8)
	s_waitcnt lgkmcnt(0)
	s_setprio 1
	s_barrier
; #define PG8_STAGE(bufoff, gbase, voff) do { _Pragma("unroll") for (int _i = 0; _i < 2; ++_i) \
;         __builtin_amdgcn_global_load_lds((const unsigned*)((const char*)(gbase) + (voff)[_i]), (PG8_LAS unsigned*)(lds + (bufoff) + ldsw + _i * 8192), 16, 0, 0); } while (0)
; #define PG8_LDA(dst, b, h) do { _Pragma("unroll") for (int m = 0; m < 4; ++m) _Pragma("unroll") for (int k = 0; k < 2; ++k) dst[m][k] = *(const PG8_LAS bf16x8*)(lds + PG8_SA(b, h) + aoff + m * 2048 + k * 1024); } while (0)
; #define PG8_LDB(dst, b, h) do { _Pragma("unroll") for (int n = 0; n < 2; ++n) _Pragma("unroll") for (int k = 0; k < 2; ++k) dst[n][k] = *(const PG8_LAS bf16x8*)(lds + PG8_SB(b, h) + boff + n * 2048 + k * 1024); } while (0)
; #define PG8_MMA(ai, bj, At, Bt) do { __builtin_amdgcn_s_setprio(1); _Pragma("unroll") for (int m = 0; m < 4; ++m) _Pragma("unroll") for (int n = 0; n < 2; ++n) _Pragma("unroll") for (int k = 0; k < 2; ++k) \
;         acc[ai][bj][m][n] = __builtin_amdgcn_mfma_f32_16x16x32_bf16(Bt[n][k], At[m][k], acc[ai][bj][m][n], 0, 0, 0); __builtin_amdgcn_s_setprio(0); } while (0)
; #define PG8_WAIT_V(n) asm volatile("s_waitcnt vmcnt(" #n ")" ::: "memory")
; #define PG8_WAIT_L(n) asm volatile("s_waitcnt lgkmcnt(" #n ")" ::: "memory")
; #define PG8_BAR __builtin_amdgcn_s_barrier()
; #define PG8_SCHED __builtin_amdgcn_sched_barrier(0)
; template <class Epi, class Sched, bool ALIGN_EPI = false, bool SP2 = false>
; __device__ __forceinline__ void gemm_phase(PG8_LAS unsigned char* lds, const Gemm g, const Sched& S, const Epi& E) {
;     ...
;             PG8_WAIT_V(8); PG8_WAIT_L(0); PG8_BAR; PG8_MMA(1, 0, At, B0); PG8_MMA(1, 1, At, B1); PG8_BAR; PG8_SCHED;
;             PG8_LDB(B0, 1, 0); PG8_LDB(B1, 1, 1); PG8_SCHED; PG8_LDA(At, 1, 0); PG8_STAGE(PG8_SA(0, 1), a2 + hstep, voffA);
;             PG8_WAIT_V(8); PG8_WAIT_L(0); PG8_BAR; PG8_MMA(0, 0, At, B0); PG8_MMA(0, 1, At, B1); PG8_BAR; PG8_SCHED;
	v_mfma_f32_16x16x32_bf16 v[62:65], v[130:133], v[210:213], 0
	v_mfma_f32_16x16x32_bf16 v[62:65], v[134:137], v[214:217], v[62:65]
	v_mfma_f32_16x16x32_bf16 v[58:61], v[138:141], v[210:213], 0
	v_mfma_f32_16x16x32_bf16 v[58:61], v[142:145], v[214:217], v[58:61]
	v_mfma_f32_16x16x32_bf16 v[46:49], v[130:133], v[218:221], 0
	v_mfma_f32_16x16x32_bf16 v[46:49], v[134:137], v[222:225], v[46:49]
	v_mfma_f32_16x16x32_bf16 v[42:45], v[138:141], v[218:221], 0
	v_mfma_f32_16x16x32_bf16 v[42:45], v[142:145], v[222:225], v[42:45]
	v_mfma_f32_16x16x32_bf16 v[30:33], v[130:133], v[226:229], 0
	v_mfma_f32_16x16x32_bf16 v[30:33], v[134:137], v[230:233], v[30:33]
	v_mfma_f32_16x16x32_bf16 v[26:29], v[138:141], v[226:229], 0
	v_mfma_f32_16x16x32_bf16 v[26:29], v[142:145], v[230:233], v[26:29]
	v_mfma_f32_16x16x32_bf16 v[14:17], v[130:133], v[234:237], 0
	v_mfma_f32_16x16x32_bf16 v[14:17], v[134:137], v[238:241], v[14:17]
	v_mfma_f32_16x16x32_bf16 v[10:13], v[138:141], v[234:237], 0
	v_mfma_f32_16x16x32_bf16 v[10:13], v[142:145], v[238:241], v[10:13]
	v_mfma_f32_16x16x32_bf16 v[54:57], v[170:173], v[210:213], 0
	v_mfma_f32_16x16x32_bf16 v[54:57], v[174:177], v[214:217], v[54:57]
	v_mfma_f32_16x16x32_bf16 v[50:53], v[202:205], v[210:213], 0
	v_mfma_f32_16x16x32_bf16 v[50:53], v[206:209], v[214:217], v[50:53]
	v_mfma_f32_16x16x32_bf16 v[38:41], v[170:173], v[218:221], 0
	v_mfma_f32_16x16x32_bf16 v[38:41], v[174:177], v[222:225], v[38:41]
	v_mfma_f32_16x16x32_bf16 v[34:37], v[202:205], v[218:221], 0
	v_mfma_f32_16x16x32_bf16 v[34:37], v[206:209], v[222:225], v[34:37]
	v_mfma_f32_16x16x32_bf16 v[22:25], v[170:173], v[226:229], 0
	v_mfma_f32_16x16x32_bf16 v[22:25], v[174:177], v[230:233], v[22:25]
	v_mfma_f32_16x16x32_bf16 v[18:21], v[202:205], v[226:229], 0
	v_mfma_f32_16x16x32_bf16 v[18:21], v[206:209], v[230:233], v[18:21]
	v_mfma_f32_16x16x32_bf16 v[6:9], v[170:173], v[234:237], 0
	v_mfma_f32_16x16x32_bf16 v[6:9], v[174:177], v[238:241], v[6:9]
	v_mfma_f32_16x16x32_bf16 v[2:5], v[202:205], v[234:237], 0
	v_mfma_f32_16x16x32_bf16 v[2:5], v[206:209], v[238:241], v[2:5]
	s_setprio 0
	s_barrier
	s_add_i32 s43, 0, 0x18000
	s_add_i32 s75, 0, 0x1c000
	v_add_u32_e32 v142, s43, v199
	v_add_u32_e32 v206, s75, v199
	ds_read_b128 v[130:133], v142
	ds_read_b128 v[134:137], v142 offset:1024
	ds_read_b128 v[138:141], v142 offset:2048
	ds_read_b128 v[142:145], v142 offset:3072
	ds_read_b128 v[170:173], v206
	ds_read_b128 v[174:177], v206 offset:1024
	ds_read_b128 v[202:205], v206 offset:2048
	ds_read_b128 v[206:209], v206 offset:3072
	s_add_u32 s14, s14, s84
	s_addc_u32 s15, s15, 0
	s_mov_b32 m0, s83
	v_lshl_add_u64 v[252:253], s[14:15], 0, v[158:159]
	ds_read_b128 v[210:213], v201 offset:32768
	ds_read_b128 v[214:217], v201 offset:33792
	ds_read_b128 v[218:221], v201 offset:34816
	ds_read_b128 v[222:225], v201 offset:35840
	ds_read_b128 v[226:229], v201 offset:36864
	ds_read_b128 v[230:233], v201 offset:37888
	ds_read_b128 v[234:237], v201 offset:38912
	ds_read_b128 v[238:241], v201 offset:39936
	global_load_lds_dwordx4 v[252:253], off
	v_lshl_add_u64 v[252:253], s[14:15], 0, v[160:161]
	s_mov_b32 m0, s24
	s_nop 0
	global_load_lds_dwordx4 v[252:253], off
	s_waitcnt vmcnt(8)
	s_waitcnt lgkmcnt(0)
	s_setprio 1
	s_barrier
	v_mfma_f32_16x16x32_bf16 v[126:129], v[130:133], v[210:213], v[126:129]
	v_mfma_f32_16x16x32_bf16 v[126:129], v[134:137], v[214:217], v[126:129]
	v_mfma_f32_16x16x32_bf16 v[122:125], v[138:141], v[210:213], v[122:125]
	v_mfma_f32_16x16x32_bf16 v[122:125], v[142:145], v[214:217], v[122:125]
	v_mfma_f32_16x16x32_bf16 v[110:113], v[130:133], v[218:221], v[110:113]
	v_mfma_f32_16x16x32_bf16 v[110:113], v[134:137], v[222:225], v[110:113]
	v_mfma_f32_16x16x32_bf16 v[106:109], v[138:141], v[218:221], v[106:109]
	v_mfma_f32_16x16x32_bf16 v[106:109], v[142:145], v[222:225], v[106:109]
	v_mfma_f32_16x16x32_bf16 v[94:97], v[130:133], v[226:229], v[94:97]
	v_mfma_f32_16x16x32_bf16 v[94:97], v[134:137], v[230:233], v[94:97]
	v_mfma_f32_16x16x32_bf16 v[90:93], v[138:141], v[226:229], v[90:93]
	v_mfma_f32_16x16x32_bf16 v[90:93], v[142:145], v[230:233], v[90:93]
	v_mfma_f32_16x16x32_bf16 v[78:81], v[130:133], v[234:237], v[78:81]
	v_mfma_f32_16x16x32_bf16 v[78:81], v[134:137], v[238:241], v[78:81]
	v_mfma_f32_16x16x32_bf16 v[74:77], v[138:141], v[234:237], v[74:77]
	v_mfma_f32_16x16x32_bf16 v[74:77], v[142:145], v[238:241], v[74:77]
	v_mfma_f32_16x16x32_bf16 v[118:121], v[170:173], v[210:213], v[118:121]
	v_mfma_f32_16x16x32_bf16 v[118:121], v[174:177], v[214:217], v[118:121]
	v_mfma_f32_16x16x32_bf16 v[114:117], v[202:205], v[210:213], v[114:117]
	v_mfma_f32_16x16x32_bf16 v[114:117], v[206:209], v[214:217], v[114:117]
	v_mfma_f32_16x16x32_bf16 v[102:105], v[170:173], v[218:221], v[102:105]
	v_mfma_f32_16x16x32_bf16 v[102:105], v[174:177], v[222:225], v[102:105]
	v_mfma_f32_16x16x32_bf16 v[98:101], v[202:205], v[218:221], v[98:101]
	v_mfma_f32_16x16x32_bf16 v[98:101], v[206:209], v[222:225], v[98:101]
	v_mfma_f32_16x16x32_bf16 v[86:89], v[170:173], v[226:229], v[86:89]
	v_mfma_f32_16x16x32_bf16 v[86:89], v[174:177], v[230:233], v[86:89]
	v_mfma_f32_16x16x32_bf16 v[82:85], v[202:205], v[226:229], v[82:85]
	v_mfma_f32_16x16x32_bf16 v[82:85], v[206:209], v[230:233], v[82:85]
	v_mfma_f32_16x16x32_bf16 v[70:73], v[170:173], v[234:237], v[70:73]
	v_mfma_f32_16x16x32_bf16 v[70:73], v[174:177], v[238:241], v[70:73]
	v_mfma_f32_16x16x32_bf16 v[66:69], v[202:205], v[234:237], v[66:69]
	v_mfma_f32_16x16x32_bf16 v[66:69], v[206:209], v[238:241], v[66:69]
	s_setprio 0
	s_barrier
; #define PG8_STAGE(bufoff, gbase, voff) do { _Pragma("unroll") for (int _i = 0; _i < 2; ++_i) \
;         __builtin_amdgcn_global_load_lds((const unsigned*)((const char*)(gbase) + (voff)[_i]), (PG8_LAS unsigned*)(lds + (bufoff) + ldsw + _i * 8192), 16, 0, 0); } while (0)
; #define PG8_LDA(dst, b, h) do { _Pragma("unroll") for (int m = 0; m < 4; ++m) _Pragma("unroll") for (int k = 0; k < 2; ++k) dst[m][k] = *(const PG8_LAS bf16x8*)(lds + PG8_SA(b, h) + aoff + m * 2048 + k * 1024); } while (0)
; #define PG8_LDB(dst, b, h) do { _Pragma("unroll") for (int n = 0; n < 2; ++n) _Pragma("unroll") for (int k = 0; k < 2; ++k) dst[n][k] = *(const PG8_LAS bf16x8*)(lds + PG8_SB(b, h) + boff + n * 2048 + k * 1024); } while (0)
; #define PG8_MMA(ai, bj, At, Bt) do { __builtin_amdgcn_s_setprio(1); _Pragma("unroll") for (int m = 0; m < 4; ++m) _Pragma("unroll") for (int n = 0; n < 2; ++n) _Pragma("unroll") for (int k = 0; k < 2; ++k) \
;         acc[ai][bj][m][n] = __builtin_amdgcn_mfma_f32_16x16x32_bf16(Bt[n][k], At[m][k], acc[ai][bj][m][n], 0, 0, 0); __builtin_amdgcn_s_setprio(0); } while (0)
; #define PG8_WAIT_V(n) asm volatile("s_waitcnt vmcnt(" #n ")" ::: "memory")
; #define PG8_WAIT_L(n) asm volatile("s_waitcnt lgkmcnt(" #n ")" ::: "memory")
; #define PG8_BAR __builtin_amdgcn_s_barrier()
; #define PG8_SCHED __builtin_amdgcn_sched_barrier(0)
; template <class Epi, class Sched, bool ALIGN_EPI = false, bool SP2 = false>
; __device__ __forceinline__ void gemm_phase(PG8_LAS unsigned char* lds, const Gemm g, const Sched& S, const Epi& E) {
;     ...
;         for (int t = 0; t < nt; t += 2) {
;             const bool last = (t == nt - 2);
;             const char* a1 = cA + (size_t)(t + 1) * kstep;
;             const char* a2 = last ? nA : cA + (size_t)(t + 2) * kstep; const char* b2 = last ? nB : cB + (size_t)(t + 2) * kstep;
;             const char* a3 = a2 + kstep; const char* b3 = b2 + kstep;
;             if (last && has_next) S.a_ready(nxt);
;             if constexpr (SP2) {
;             PG8_LDB(B0, 0, 0); PG8_LDB(B1, 0, 1); PG8_SCHED; PG8_LDA(At, 0, 0); PG8_STAGE(PG8_SA(1, 1), a1 + hstep, voffA);
;     ...
;             PG8_LDA(At, 1, 1); PG8_STAGE(PG8_SB(1, 0), b3, voffB); PG8_STAGE(PG8_SB(1, 1), b3 + hstep, voffB); PG8_STAGE(PG8_SA(1, 0), a3, voffA);
;             PG8_WAIT_V(8); PG8_WAIT_L(0); PG8_BAR; PG8_MMA(1, 0, At, B0); PG8_MMA(1, 1, At, B1); PG8_BAR; PG8_SCHED;
	s_add_i32 s14, s43, s23
	v_lshl_add_u64 v[178:179], v[178:179], 0, s[94:95]
	s_mov_b32 m0, s14
	ds_read_b128 v[210:213], v201 offset:49152
	ds_read_b128 v[214:217], v201 offset:50176
	ds_read_b128 v[218:221], v201 offset:51200
	ds_read_b128 v[222:225], v201 offset:52224
	ds_read_b128 v[226:229], v201 offset:53248
	ds_read_b128 v[230:233], v201 offset:54272
	ds_read_b128 v[234:237], v201 offset:55296
	ds_read_b128 v[238:241], v201 offset:56320
	global_load_lds_dwordx4 v[178:179], off
	v_lshl_add_u64 v[178:179], v[242:243], 0, s[94:95]
	s_add_i32 m0, s14, 0x2000
	s_add_i32 s14, s75, s23
	global_load_lds_dwordx4 v[178:179], off
	v_lshl_add_u64 v[178:179], v[244:245], 0, s[94:95]
	s_mov_b32 m0, s14
	s_nop 0
	global_load_lds_dwordx4 v[178:179], off
	v_lshl_add_u64 v[178:179], v[246:247], 0, s[94:95]
	s_add_i32 m0, s14, 0x2000
	s_nop 0
	global_load_lds_dwordx4 v[178:179], off
	v_lshl_add_u64 v[178:179], v[248:249], 0, s[94:95]
	s_mov_b32 m0, s63
	s_nop 0
	global_load_lds_dwordx4 v[178:179], off
	v_lshl_add_u64 v[178:179], v[250:251], 0, s[94:95]
	s_mov_b32 m0, s70
	s_nop 0
	global_load_lds_dwordx4 v[178:179], off
	s_waitcnt vmcnt(8)
	s_waitcnt lgkmcnt(0)
	s_setprio 1
	s_barrier
	v_mfma_f32_16x16x32_bf16 v[62:65], v[130:133], v[210:213], v[62:65]
	v_mfma_f32_16x16x32_bf16 v[62:65], v[134:137], v[214:217], v[62:65]
	v_mfma_f32_16x16x32_bf16 v[58:61], v[138:141], v[210:213], v[58:61]
	v_mfma_f32_16x16x32_bf16 v[58:61], v[142:145], v[214:217], v[58:61]
	v_mfma_f32_16x16x32_bf16 v[46:49], v[130:133], v[218:221], v[46:49]
	v_mfma_f32_16x16x32_bf16 v[46:49], v[134:137], v[222:225], v[46:49]
	v_mfma_f32_16x16x32_bf16 v[42:45], v[138:141], v[218:221], v[42:45]
	v_mfma_f32_16x16x32_bf16 v[42:45], v[142:145], v[222:225], v[42:45]
	v_mfma_f32_16x16x32_bf16 v[30:33], v[130:133], v[226:229], v[30:33]
	v_mfma_f32_16x16x32_bf16 v[30:33], v[134:137], v[230:233], v[30:33]
	v_mfma_f32_16x16x32_bf16 v[26:29], v[138:141], v[226:229], v[26:29]
	v_mfma_f32_16x16x32_bf16 v[26:29], v[142:145], v[230:233], v[26:29]
	v_mfma_f32_16x16x32_bf16 v[14:17], v[130:133], v[234:237], v[14:17]
	v_mfma_f32_16x16x32_bf16 v[14:17], v[134:137], v[238:241], v[14:17]
	v_mfma_f32_16x16x32_bf16 v[10:13], v[138:141], v[234:237], v[10:13]
	v_mfma_f32_16x16x32_bf16 v[10:13], v[142:145], v[238:241], v[10:13]
	v_mfma_f32_16x16x32_bf16 v[54:57], v[170:173], v[210:213], v[54:57]
	v_mfma_f32_16x16x32_bf16 v[54:57], v[174:177], v[214:217], v[54:57]
	v_mfma_f32_16x16x32_bf16 v[50:53], v[202:205], v[210:213], v[50:53]
	v_mfma_f32_16x16x32_bf16 v[50:53], v[206:209], v[214:217], v[50:53]
	v_mfma_f32_16x16x32_bf16 v[38:41], v[170:173], v[218:221], v[38:41]
	v_mfma_f32_16x16x32_bf16 v[38:41], v[174:177], v[222:225], v[38:41]
	v_mfma_f32_16x16x32_bf16 v[34:37], v[202:205], v[218:221], v[34:37]
	v_mfma_f32_16x16x32_bf16 v[34:37], v[206:209], v[222:225], v[34:37]
	v_mfma_f32_16x16x32_bf16 v[22:25], v[170:173], v[226:229], v[22:25]
	v_mfma_f32_16x16x32_bf16 v[22:25], v[174:177], v[230:233], v[22:25]
	v_mfma_f32_16x16x32_bf16 v[18:21], v[202:205], v[226:229], v[18:21]
	v_mfma_f32_16x16x32_bf16 v[18:21], v[206:209], v[230:233], v[18:21]
	v_mfma_f32_16x16x32_bf16 v[6:9], v[170:173], v[234:237], v[6:9]
	v_mfma_f32_16x16x32_bf16 v[6:9], v[174:177], v[238:241], v[6:9]
	v_mfma_f32_16x16x32_bf16 v[2:5], v[202:205], v[234:237], v[2:5]
	v_mfma_f32_16x16x32_bf16 v[2:5], v[206:209], v[238:241], v[2:5]
	s_setprio 0
	s_barrier
	s_add_u32 s12, s12, 0x100
	s_addc_u32 s13, s13, 0
	s_add_u32 s16, s16, 0x100
	s_addc_u32 s17, s17, 0
	s_cmp_ge_u32 s42, s28
	s_mov_b32 s14, s42
	s_cbranch_scc0 .LBB0_322
	s_branch .Lk_done
.LBB0_322:
	s_add_i32 s42, s14, 2
	s_add_u32 s43, s12, 0x80
	s_addc_u32 s15, s13, 0
	s_add_i32 s75, 0, 0x10000
	s_cmp_eq_u32 s25, s14
	s_cselect_b32 s15, s55, s15
	s_cselect_b32 s14, s54, s43
	s_cselect_b32 vcc_hi, s65, s17
	s_cselect_b32 vcc_lo, s64, s16
	s_add_i32 s43, 0, 0x14000
	v_add_u32_e32 v142, s75, v199
	v_add_u32_e32 v178, s43, v199
	ds_read_b128 v[130:133], v142
	ds_read_b128 v[134:137], v142 offset:1024
	ds_read_b128 v[138:141], v142 offset:2048
	ds_read_b128 v[142:145], v142 offset:3072
	ds_read_b128 v[170:173], v178
	ds_read_b128 v[174:177], v178 offset:1024
	ds_read_b128 v[202:205], v178 offset:2048
	ds_read_b128 v[206:209], v178 offset:3072
	v_lshl_add_u64 v[178:179], s[12:13], 0, v[166:167]
	s_add_i32 m0, s56, 0xc000
	ds_read_b128 v[210:213], v201
	ds_read_b128 v[214:217], v201 offset:1024
	ds_read_b128 v[218:221], v201 offset:2048
	ds_read_b128 v[222:225], v201 offset:3072
	ds_read_b128 v[226:229], v201 offset:4096
	ds_read_b128 v[230:233], v201 offset:5120
	ds_read_b128 v[234:237], v201 offset:6144
	ds_read_b128 v[238:241], v201 offset:7168
	global_load_lds_dwordx4 v[178:179], off
	v_lshl_add_u64 v[178:179], s[12:13], 0, v[168:169]
	s_add_i32 m0, s56, 0xe000
	s_nop 0
	global_load_lds_dwordx4 v[178:179], off
	s_waitcnt vmcnt(8)
	s_waitcnt lgkmcnt(0)
	s_setprio 1
	s_barrier
; #define PG8_STAGE(bufoff, gbase, voff) do { _Pragma("unroll") for (int _i = 0; _i < 2; ++_i) \
;         __builtin_amdgcn_global_load_lds((const unsigned*)((const char*)(gbase) + (voff)[_i]), (PG8_LAS unsigned*)(lds + (bufoff) + ldsw + _i * 8192), 16, 0, 0); } while (0)
; #define PG8_LDA(dst, b, h) do { _Pragma("unroll") for (int m = 0; m < 4; ++m) _Pragma("unroll") for (int k = 0; k < 2; ++k) dst[m][k] = *(const PG8_LAS bf16x8*)(lds + PG8_SA(b, h) + aoff + m * 2048 + k * 1024); } while (0)
; #define PG8_LDB(dst, b, h) do { _Pragma("unroll") for (int n = 0; n < 2; ++n) _Pragma("unroll") for (int k = 0; k < 2; ++k) dst[n][k] = *(const PG8_LAS bf16x8*)(lds + PG8_SB(b, h) + boff + n * 2048 + k * 1024); } while (0)
; #define PG8_MMA(ai, bj, At, Bt) do { __builtin_amdgcn_s_setprio(1); _Pragma("unroll") for (int m = 0; m < 4; ++m) _Pragma("unroll") for (int n = 0; n < 2; ++n) _Pragma("unroll") for (int k = 0; k < 2; ++k) \
;         acc[ai][bj][m][n] = __builtin_amdgcn_mfma_f32_16x16x32_bf16(Bt[n][k], At[m][k], acc[ai][bj][m][n], 0, 0, 0); __builtin_amdgcn_s_setprio(0); } while (0)
; #define PG8_WAIT_V(n) asm volatile("s_waitcnt vmcnt(" #n ")" ::: "memory")
; #define PG8_WAIT_L(n) asm volatile("s_waitcnt lgkmcnt(" #n ")" ::: "memory")
; #define PG8_BAR __builtin_amdgcn_s_barrier()
; #define PG8_SCHED __builtin_amdgcn_sched_barrier(0)
; template <class Epi, class Sched, bool ALIGN_EPI = false, bool SP2 = false>
; __device__ __forceinline__ void gemm_phase(PG8_LAS unsigned char* lds, const Gemm g, const Sched& S, const Epi& E) {
;     ...
;             PG8_LDB(B0, 0, 0); PG8_LDB(B1, 0, 1); PG8_SCHED; PG8_LDA(At, 0, 0); PG8_STAGE(PG8_SA(1, 1), a1 + hstep, voffA);
;             PG8_WAIT_V(8); PG8_WAIT_L(0); PG8_BAR; PG8_MMA(0, 0, At, B0); PG8_MMA(0, 1, At, B1); PG8_BAR; PG8_SCHED;
;             PG8_LDA(At, 0, 1); PG8_STAGE(PG8_SB(0, 0), b2, voffB); PG8_STAGE(PG8_SB(0, 1), b2 + hstep, voffB); PG8_STAGE(PG8_SA(0, 0), a2, voffA);
;             PG8_WAIT_V(8); PG8_WAIT_L(0); PG8_BAR; PG8_MMA(1, 0, At, B0); PG8_MMA(1, 1, At, B1); PG8_BAR; PG8_SCHED;
	v_mfma_f32_16x16x32_bf16 v[126:129], v[130:133], v[210:213], v[126:129]
	v_mfma_f32_16x16x32_bf16 v[126:129], v[134:137], v[214:217], v[126:129]
	v_mfma_f32_16x16x32_bf16 v[122:125], v[138:141], v[210:213], v[122:125]
	v_mfma_f32_16x16x32_bf16 v[122:125], v[142:145], v[214:217], v[122:125]
	v_mfma_f32_16x16x32_bf16 v[110:113], v[130:133], v[218:221], v[110:113]
	v_mfma_f32_16x16x32_bf16 v[110:113], v[134:137], v[222:225], v[110:113]
	v_mfma_f32_16x16x32_bf16 v[106:109], v[138:141], v[218:221], v[106:109]
	v_mfma_f32_16x16x32_bf16 v[106:109], v[142:145], v[222:225], v[106:109]
	v_mfma_f32_16x16x32_bf16 v[94:97], v[130:133], v[226:229], v[94:97]
	v_mfma_f32_16x16x32_bf16 v[94:97], v[134:137], v[230:233], v[94:97]
	v_mfma_f32_16x16x32_bf16 v[90:93], v[138:141], v[226:229], v[90:93]
	v_mfma_f32_16x16x32_bf16 v[90:93], v[142:145], v[230:233], v[90:93]
	v_mfma_f32_16x16x32_bf16 v[78:81], v[130:133], v[234:237], v[78:81]
	v_mfma_f32_16x16x32_bf16 v[78:81], v[134:137], v[238:241], v[78:81]
	v_mfma_f32_16x16x32_bf16 v[74:77], v[138:141], v[234:237], v[74:77]
	v_mfma_f32_16x16x32_bf16 v[74:77], v[142:145], v[238:241], v[74:77]
	v_mfma_f32_16x16x32_bf16 v[118:121], v[170:173], v[210:213], v[118:121]
	v_mfma_f32_16x16x32_bf16 v[118:121], v[174:177], v[214:217], v[118:121]
	v_mfma_f32_16x16x32_bf16 v[114:117], v[202:205], v[210:213], v[114:117]
	v_mfma_f32_16x16x32_bf16 v[114:117], v[206:209], v[214:217], v[114:117]
	v_mfma_f32_16x16x32_bf16 v[102:105], v[170:173], v[218:221], v[102:105]
	v_mfma_f32_16x16x32_bf16 v[102:105], v[174:177], v[222:225], v[102:105]
	v_mfma_f32_16x16x32_bf16 v[98:101], v[202:205], v[218:221], v[98:101]
	v_mfma_f32_16x16x32_bf16 v[98:101], v[206:209], v[222:225], v[98:101]
	v_mfma_f32_16x16x32_bf16 v[86:89], v[170:173], v[226:229], v[86:89]
	v_mfma_f32_16x16x32_bf16 v[86:89], v[174:177], v[230:233], v[86:89]
	v_mfma_f32_16x16x32_bf16 v[82:85], v[202:205], v[226:229], v[82:85]
	v_mfma_f32_16x16x32_bf16 v[82:85], v[206:209], v[230:233], v[82:85]
	v_mfma_f32_16x16x32_bf16 v[70:73], v[170:173], v[234:237], v[70:73]
	v_mfma_f32_16x16x32_bf16 v[70:73], v[174:177], v[238:241], v[70:73]
	v_mfma_f32_16x16x32_bf16 v[66:69], v[202:205], v[234:237], v[66:69]
	v_mfma_f32_16x16x32_bf16 v[66:69], v[206:209], v[238:241], v[66:69]
	s_setprio 0
	s_barrier
	s_add_i32 s75, s75, s23
	v_lshl_add_u64 v[178:179], vcc, 0, v[0:1]
	s_mov_b32 m0, s75
	ds_read_b128 v[210:213], v201 offset:16384
	ds_read_b128 v[214:217], v201 offset:17408
	ds_read_b128 v[218:221], v201 offset:18432
	ds_read_b128 v[222:225], v201 offset:19456
	ds_read_b128 v[226:229], v201 offset:20480
	ds_read_b128 v[230:233], v201 offset:21504
	ds_read_b128 v[234:237], v201 offset:22528
	ds_read_b128 v[238:241], v201 offset:23552
	global_load_lds_dwordx4 v[178:179], off
	s_add_i32 m0, s75, 0x2000
	v_lshl_add_u64 v[242:243], vcc, 0, v[162:163]
	s_add_u32 vcc_lo, vcc_lo, s84
	s_addc_u32 vcc_hi, vcc_hi, 0
	s_add_i32 s43, s43, s23
	global_load_lds_dwordx4 v[242:243], off
	v_lshl_add_u64 v[244:245], vcc, 0, v[0:1]
	s_mov_b32 m0, s43
	v_lshl_add_u64 v[246:247], vcc, 0, v[162:163]
	global_load_lds_dwordx4 v[244:245], off
	s_add_i32 m0, s43, 0x2000
	v_lshl_add_u64 v[248:249], s[14:15], 0, v[158:159]
	global_load_lds_dwordx4 v[246:247], off
	s_mov_b32 m0, s56
	v_lshl_add_u64 v[250:251], s[14:15], 0, v[160:161]
	global_load_lds_dwordx4 v[248:249], off
	s_mov_b32 m0, s82
	s_nop 0
	global_load_lds_dwordx4 v[250:251], off
	s_waitcnt vmcnt(8)
	s_waitcnt lgkmcnt(0)
	s_setprio 1
	s_barrier
	v_mfma_f32_16x16x32_bf16 v[62:65], v[130:133], v[210:213], v[62:65]
	v_mfma_f32_16x16x32_bf16 v[62:65], v[134:137], v[214:217], v[62:65]
	v_mfma_f32_16x16x32_bf16 v[58:61], v[138:141], v[210:213], v[58:61]
	v_mfma_f32_16x16x32_bf16 v[58:61], v[142:145], v[214:217], v[58:61]
	v_mfma_f32_16x16x32_bf16 v[46:49], v[130:133], v[218:221], v[46:49]
	v_mfma_f32_16x16x32_bf16 v[46:49], v[134:137], v[222:225], v[46:49]
	v_mfma_f32_16x16x32_bf16 v[42:45], v[138:141], v[218:221], v[42:45]
	v_mfma_f32_16x16x32_bf16 v[42:45], v[142:145], v[222:225], v[42:45]
	v_mfma_f32_16x16x32_bf16 v[30:33], v[130:133], v[226:229], v[30:33]
	v_mfma_f32_16x16x32_bf16 v[30:33], v[134:137], v[230:233], v[30:33]
	v_mfma_f32_16x16x32_bf16 v[26:29], v[138:141], v[226:229], v[26:29]
	v_mfma_f32_16x16x32_bf16 v[26:29], v[142:145], v[230:233], v[26:29]
	v_mfma_f32_16x16x32_bf16 v[14:17], v[130:133], v[234:237], v[14:17]
	v_mfma_f32_16x16x32_bf16 v[14:17], v[134:137], v[238:241], v[14:17]
	v_mfma_f32_16x16x32_bf16 v[10:13], v[138:141], v[234:237], v[10:13]
	v_mfma_f32_16x16x32_bf16 v[10:13], v[142:145], v[238:241], v[10:13]
	v_mfma_f32_16x16x32_bf16 v[54:57], v[170:173], v[210:213], v[54:57]
	v_mfma_f32_16x16x32_bf16 v[54:57], v[174:177], v[214:217], v[54:57]
	v_mfma_f32_16x16x32_bf16 v[50:53], v[202:205], v[210:213], v[50:53]
	v_mfma_f32_16x16x32_bf16 v[50:53], v[206:209], v[214:217], v[50:53]
	v_mfma_f32_16x16x32_bf16 v[38:41], v[170:173], v[218:221], v[38:41]
	v_mfma_f32_16x16x32_bf16 v[38:41], v[174:177], v[222:225], v[38:41]
	v_mfma_f32_16x16x32_bf16 v[34:37], v[202:205], v[218:221], v[34:37]
	v_mfma_f32_16x16x32_bf16 v[34:37], v[206:209], v[222:225], v[34:37]
	v_mfma_f32_16x16x32_bf16 v[22:25], v[170:173], v[226:229], v[22:25]
	v_mfma_f32_16x16x32_bf16 v[22:25], v[174:177], v[230:233], v[22:25]
	v_mfma_f32_16x16x32_bf16 v[18:21], v[202:205], v[226:229], v[18:21]
	v_mfma_f32_16x16x32_bf16 v[18:21], v[206:209], v[230:233], v[18:21]
	v_mfma_f32_16x16x32_bf16 v[6:9], v[170:173], v[234:237], v[6:9]
	v_mfma_f32_16x16x32_bf16 v[6:9], v[174:177], v[238:241], v[6:9]
	v_mfma_f32_16x16x32_bf16 v[2:5], v[202:205], v[234:237], v[2:5]
	v_mfma_f32_16x16x32_bf16 v[2:5], v[206:209], v[238:241], v[2:5]
	s_setprio 0
	s_barrier
; #define PG8_STAGE(bufoff, gbase, voff) do { _Pragma("unroll") for (int _i = 0; _i < 2; ++_i) \
;         __builtin_amdgcn_global_load_lds((const unsigned*)((const char*)(gbase) + (voff)[_i]), (PG8_LAS unsigned*)(lds + (bufoff) + ldsw + _i * 8192), 16, 0, 0); } while (0)
; #define PG8_LDA(dst, b, h) do { _Pragma("unroll") for (int m = 0; m < 4; ++m) _Pragma("unroll") for (int k = 0; k < 2; ++k) dst[m][k] = *(const PG8_LAS bf16x8*)(lds + PG8_SA(b, h) + aoff + m * 2048 + k * 1024); } while (0)
; #define PG8_LDB(dst, b, h) do { _Pragma("unroll") for (int n = 0; n < 2; ++n) _Pragma("unroll") for (int k = 0; k < 2; ++k) dst[n][k] = *(const PG8_LAS bf16x8*)(lds + PG8_SB(b, h) + boff + n * 2048 + k * 1024); } while (0)
; #define PG8_MMA(ai, bj, At, Bt) do { __builtin_amdgcn_s_setprio(1); _Pragma("unroll") for (int m = 0; m < 4; ++m) _Pragma("unroll") for (int n = 0; n < 2; ++n) _Pragma("unroll") for (int k = 0; k < 2; ++k) \
;         acc[ai][bj][m][n] = __builtin_amdgcn_mfma_f32_16x16x32_bf16(Bt[n][k], At[m][k], acc[ai][bj][m][n], 0, 0, 0); __builtin_amdgcn_s_setprio(0); } while (0)
; #define PG8_WAIT_V(n) asm volatile("s_waitcnt vmcnt(" #n ")" ::: "memory")
; #define PG8_WAIT_L(n) asm volatile("s_waitcnt lgkmcnt(" #n ")" ::: "memory")
; #define PG8_BAR __builtin_amdgcn_s_barrier()
; #define PG8_SCHED __builtin_amdgcn_sched_barrier(0)
; template <class Epi, class Sched, bool ALIGN_EPI = false, bool SP2 = false>
; __device__ __forceinline__ void gemm_phase(PG8_LAS unsigned char* lds, const Gemm g, const Sched& S, const Epi& E) {
;     ...
;             PG8_LDB(B0, 1, 0); PG8_LDB(B1, 1, 1); PG8_SCHED; PG8_LDA(At, 1, 0); PG8_STAGE(PG8_SA(0, 1), a2 + hstep, voffA);
;             PG8_WAIT_V(8); PG8_WAIT_L(0); PG8_BAR; PG8_MMA(0, 0, At, B0); PG8_MMA(0, 1, At, B1); PG8_BAR; PG8_SCHED;
;             PG8_LDA(At, 1, 1); PG8_STAGE(PG8_SB(1, 0), b3, voffB); PG8_STAGE(PG8_SB(1, 1), b3 + hstep, voffB); PG8_STAGE(PG8_SA(1, 0), a3, voffA);
;             PG8_WAIT_V(8); PG8_WAIT_L(0); PG8_BAR; PG8_MMA(1, 0, At, B0); PG8_MMA(1, 1, At, B1); PG8_BAR; PG8_SCHED;
	s_add_i32 s43, 0, 0x18000
	s_add_i32 s75, 0, 0x1c000
	v_add_u32_e32 v142, s43, v199
	v_add_u32_e32 v206, s75, v199
	ds_read_b128 v[130:133], v142
	ds_read_b128 v[134:137], v142 offset:1024
	ds_read_b128 v[138:141], v142 offset:2048
	ds_read_b128 v[142:145], v142 offset:3072
	ds_read_b128 v[170:173], v206
	ds_read_b128 v[174:177], v206 offset:1024
	ds_read_b128 v[202:205], v206 offset:2048
	ds_read_b128 v[206:209], v206 offset:3072
	s_add_u32 s14, s14, s84
	s_addc_u32 s15, s15, 0
	s_mov_b32 m0, s83
	v_lshl_add_u64 v[252:253], s[14:15], 0, v[158:159]
	ds_read_b128 v[210:213], v201 offset:32768
	ds_read_b128 v[214:217], v201 offset:33792
	ds_read_b128 v[218:221], v201 offset:34816
	ds_read_b128 v[222:225], v201 offset:35840
	ds_read_b128 v[226:229], v201 offset:36864
	ds_read_b128 v[230:233], v201 offset:37888
	ds_read_b128 v[234:237], v201 offset:38912
	ds_read_b128 v[238:241], v201 offset:39936
	global_load_lds_dwordx4 v[252:253], off
	v_lshl_add_u64 v[252:253], s[14:15], 0, v[160:161]
	s_mov_b32 m0, s24
	s_nop 0
	global_load_lds_dwordx4 v[252:253], off
	s_waitcnt vmcnt(8)
	s_waitcnt lgkmcnt(0)
	s_setprio 1
	s_barrier
	v_mfma_f32_16x16x32_bf16 v[126:129], v[130:133], v[210:213], v[126:129]
	v_mfma_f32_16x16x32_bf16 v[126:129], v[134:137], v[214:217], v[126:129]
	v_mfma_f32_16x16x32_bf16 v[122:125], v[138:141], v[210:213], v[122:125]
	v_mfma_f32_16x16x32_bf16 v[122:125], v[142:145], v[214:217], v[122:125]
	v_mfma_f32_16x16x32_bf16 v[110:113], v[130:133], v[218:221], v[110:113]
	v_mfma_f32_16x16x32_bf16 v[110:113], v[134:137], v[222:225], v[110:113]
	v_mfma_f32_16x16x32_bf16 v[106:109], v[138:141], v[218:221], v[106:109]
	v_mfma_f32_16x16x32_bf16 v[106:109], v[142:145], v[222:225], v[106:109]
	v_mfma_f32_16x16x32_bf16 v[94:97], v[130:133], v[226:229], v[94:97]
	v_mfma_f32_16x16x32_bf16 v[94:97], v[134:137], v[230:233], v[94:97]
	v_mfma_f32_16x16x32_bf16 v[90:93], v[138:141], v[226:229], v[90:93]
	v_mfma_f32_16x16x32_bf16 v[90:93], v[142:145], v[230:233], v[90:93]
	v_mfma_f32_16x16x32_bf16 v[78:81], v[130:133], v[234:237], v[78:81]
	v_mfma_f32_16x16x32_bf16 v[78:81], v[134:137], v[238:241], v[78:81]
	v_mfma_f32_16x16x32_bf16 v[74:77], v[138:141], v[234:237], v[74:77]
	v_mfma_f32_16x16x32_bf16 v[74:77], v[142:145], v[238:241], v[74:77]
	v_mfma_f32_16x16x32_bf16 v[118:121], v[170:173], v[210:213], v[118:121]
	v_mfma_f32_16x16x32_bf16 v[118:121], v[174:177], v[214:217], v[118:121]
	v_mfma_f32_16x16x32_bf16 v[114:117], v[202:205], v[210:213], v[114:117]
	v_mfma_f32_16x16x32_bf16 v[114:117], v[206:209], v[214:217], v[114:117]
	v_mfma_f32_16x16x32_bf16 v[102:105], v[170:173], v[218:221], v[102:105]
	v_mfma_f32_16x16x32_bf16 v[102:105], v[174:177], v[222:225], v[102:105]
	v_mfma_f32_16x16x32_bf16 v[98:101], v[202:205], v[218:221], v[98:101]
	v_mfma_f32_16x16x32_bf16 v[98:101], v[206:209], v[222:225], v[98:101]
	v_mfma_f32_16x16x32_bf16 v[86:89], v[170:173], v[226:229], v[86:89]
	v_mfma_f32_16x16x32_bf16 v[86:89], v[174:177], v[230:233], v[86:89]
	v_mfma_f32_16x16x32_bf16 v[82:85], v[202:205], v[226:229], v[82:85]
	v_mfma_f32_16x16x32_bf16 v[82:85], v[206:209], v[230:233], v[82:85]
	v_mfma_f32_16x16x32_bf16 v[70:73], v[170:173], v[234:237], v[70:73]
	v_mfma_f32_16x16x32_bf16 v[70:73], v[174:177], v[238:241], v[70:73]
	v_mfma_f32_16x16x32_bf16 v[66:69], v[202:205], v[234:237], v[66:69]
	v_mfma_f32_16x16x32_bf16 v[66:69], v[206:209], v[238:241], v[66:69]
	s_setprio 0
	s_barrier
	s_add_i32 s14, s43, s23
	v_lshl_add_u64 v[178:179], v[178:179], 0, s[94:95]
	s_mov_b32 m0, s14
	ds_read_b128 v[210:213], v201 offset:49152
	ds_read_b128 v[214:217], v201 offset:50176
	ds_read_b128 v[218:221], v201 offset:51200
	ds_read_b128 v[222:225], v201 offset:52224
	ds_read_b128 v[226:229], v201 offset:53248
	ds_read_b128 v[230:233], v201 offset:54272
	ds_read_b128 v[234:237], v201 offset:55296
	ds_read_b128 v[238:241], v201 offset:56320
	global_load_lds_dwordx4 v[178:179], off
	v_lshl_add_u64 v[178:179], v[242:243], 0, s[94:95]
	s_add_i32 m0, s14, 0x2000
	s_add_i32 s14, s75, s23
	global_load_lds_dwordx4 v[178:179], off
	v_lshl_add_u64 v[178:179], v[244:245], 0, s[94:95]
	s_mov_b32 m0, s14
	s_nop 0
	global_load_lds_dwordx4 v[178:179], off
	v_lshl_add_u64 v[178:179], v[246:247], 0, s[94:95]
	s_add_i32 m0, s14, 0x2000
	s_nop 0
	global_load_lds_dwordx4 v[178:179], off
	v_lshl_add_u64 v[178:179], v[248:249], 0, s[94:95]
	s_mov_b32 m0, s63
	s_nop 0
	global_load_lds_dwordx4 v[178:179], off
	v_lshl_add_u64 v[178:179], v[250:251], 0, s[94:95]
	s_mov_b32 m0, s70
	s_nop 0
	global_load_lds_dwordx4 v[178:179], off
	s_waitcnt vmcnt(8)
	s_waitcnt lgkmcnt(0)
	s_setprio 1
	s_barrier
	v_mfma_f32_16x16x32_bf16 v[62:65], v[130:133], v[210:213], v[62:65]
	v_mfma_f32_16x16x32_bf16 v[62:65], v[134:137], v[214:217], v[62:65]
	v_mfma_f32_16x16x32_bf16 v[58:61], v[138:141], v[210:213], v[58:61]
	v_mfma_f32_16x16x32_bf16 v[58:61], v[142:145], v[214:217], v[58:61]
	v_mfma_f32_16x16x32_bf16 v[46:49], v[130:133], v[218:221], v[46:49]
	v_mfma_f32_16x16x32_bf16 v[46:49], v[134:137], v[222:225], v[46:49]
	v_mfma_f32_16x16x32_bf16 v[42:45], v[138:141], v[218:221], v[42:45]
	v_mfma_f32_16x16x32_bf16 v[42:45], v[142:145], v[222:225], v[42:45]
	v_mfma_f32_16x16x32_bf16 v[30:33], v[130:133], v[226:229], v[30:33]
	v_mfma_f32_16x16x32_bf16 v[30:33], v[134:137], v[230:233], v[30:33]
	v_mfma_f32_16x16x32_bf16 v[26:29], v[138:141], v[226:229], v[26:29]
	v_mfma_f32_16x16x32_bf16 v[26:29], v[142:145], v[230:233], v[26:29]
	v_mfma_f32_16x16x32_bf16 v[14:17], v[130:133], v[234:237], v[14:17]
	v_mfma_f32_16x16x32_bf16 v[14:17], v[134:137], v[238:241], v[14:17]
	v_mfma_f32_16x16x32_bf16 v[10:13], v[138:141], v[234:237], v[10:13]
	v_mfma_f32_16x16x32_bf16 v[10:13], v[142:145], v[238:241], v[10:13]
	v_mfma_f32_16x16x32_bf16 v[54:57], v[170:173], v[210:213], v[54:57]
	v_mfma_f32_16x16x32_bf16 v[54:57], v[174:177], v[214:217], v[54:57]
	v_mfma_f32_16x16x32_bf16 v[50:53], v[202:205], v[210:213], v[50:53]
	v_mfma_f32_16x16x32_bf16 v[50:53], v[206:209], v[214:217], v[50:53]
	v_mfma_f32_16x16x32_bf16 v[38:41], v[170:173], v[218:221], v[38:41]
	v_mfma_f32_16x16x32_bf16 v[38:41], v[174:177], v[222:225], v[38:41]
	v_mfma_f32_16x16x32_bf16 v[34:37], v[202:205], v[218:221], v[34:37]
	v_mfma_f32_16x16x32_bf16 v[34:37], v[206:209], v[222:225], v[34:37]
	v_mfma_f32_16x16x32_bf16 v[22:25], v[170:173], v[226:229], v[22:25]
	v_mfma_f32_16x16x32_bf16 v[22:25], v[174:177], v[230:233], v[22:25]
	v_mfma_f32_16x16x32_bf16 v[18:21], v[202:205], v[226:229], v[18:21]
	v_mfma_f32_16x16x32_bf16 v[18:21], v[206:209], v[230:233], v[18:21]
	v_mfma_f32_16x16x32_bf16 v[6:9], v[170:173], v[234:237], v[6:9]
	v_mfma_f32_16x16x32_bf16 v[6:9], v[174:177], v[238:241], v[6:9]
	v_mfma_f32_16x16x32_bf16 v[2:5], v[202:205], v[234:237], v[2:5]
	v_mfma_f32_16x16x32_bf16 v[2:5], v[206:209], v[238:241], v[2:5]
	s_setprio 0
	s_barrier
	s_add_u32 s12, s12, 0x100
	s_addc_u32 s13, s13, 0
	s_add_u32 s16, s16, 0x100
	s_addc_u32 s17, s17, 0
	s_cmp_ge_u32 s42, s28
	s_mov_b32 s14, s42
	s_cbranch_scc0 .LBB0_322
